# v044 plus the same 7.11 loop-edge rotation on the FFN-down/out-projection K-loop
# speedup vs baseline: 1.0004x; 1.0004x over previous
; #define PG8_STAGE(bufoff, gbase, voff) do { _Pragma("unroll") for (int _i = 0; _i < 2; ++_i) \
;         __builtin_amdgcn_global_load_lds((const unsigned*)((const char*)(gbase) + (voff)[_i]), (LAS unsigned*)(lds + (bufoff) + ldsw + _i * 8192), 16, 0, 0); } while (0)
; #define PG8_LDA(dst, b, h) do { _Pragma("unroll") for (int m = 0; m < 4; ++m) _Pragma("unroll") for (int k = 0; k < 2; ++k) dst[m][k] = *(const LAS bf16x8*)(lds + PG8_SA(b, h) + aoff + m * 2048 + k * 1024); } while (0)
; #define PG8_LDB(dst, b, h) do { _Pragma("unroll") for (int n = 0; n < 2; ++n) _Pragma("unroll") for (int k = 0; k < 2; ++k) dst[n][k] = *(const LAS bf16x8*)(lds + PG8_SB(b, h) + boff + n * 2048 + k * 1024); } while (0)
; #define PG8_MMA(ai, bj, At, Bt) do { __builtin_amdgcn_s_setprio(1); _Pragma("unroll") for (int m = 0; m < 4; ++m) _Pragma("unroll") for (int n = 0; n < 2; ++n) _Pragma("unroll") for (int k = 0; k < 2; ++k) \
;         acc[ai][bj][m][n] = __builtin_amdgcn_mfma_f32_16x16x32_bf16(Bt[n][k], At[m][k], acc[ai][bj][m][n], 0, 0, 0); __builtin_amdgcn_s_setprio(0); } while (0)
; #define PG8_WAIT_V(n) asm volatile("s_waitcnt vmcnt(" #n ")" ::: "memory")
; #define PG8_WAIT_L(n) asm volatile("s_waitcnt lgkmcnt(" #n ")" ::: "memory")
; #define PG8_BAR __builtin_amdgcn_s_barrier()
; #define PG8_SCHED __builtin_amdgcn_sched_barrier(0)
; template <class Epi, bool ALIGN_EPI, bool SP2, bool ROWHALF = false>
; DI void gemm_phase(LAS unsigned char* lds, const Gemm g, const StaticOrder& S, const Epi& E) {
;     ...
;         for (int t = 0; t < nt; t += 2) {
;             const bool last = (t == nt - 2);
;             const char* a1 = cA + (size_t)(t + 1) * kstep;
;             const char* a2 = last ? nA : cA + (size_t)(t + 2) * kstep; const char* b2 = last ? nB : cB + (size_t)(t + 2) * kstep;
;             const char* a3 = a2 + kstep; const char* b3 = b2 + kstep;
;             if constexpr (SP2) {
;             PG8_LDB(B0, 0, 0); PG8_LDB(B1, 0, 1); PG8_SCHED; PG8_LDA(At, 0, 0); PG8_STAGE(PG8_SA(1, 1), a1 + hA1, voffA);
;             PG8_WAIT_V(8); PG8_WAIT_L(0); PG8_BAR; PG8_MMA(0, 0, At, B0); PG8_MMA(0, 1, At, B1); PG8_BAR; PG8_SCHED;
;             if constexpr (!ROWHALF) { PG8_LDA(At, 0, 1); } PG8_STAGE(PG8_SB(0, 0), b2, voffB); PG8_STAGE(PG8_SB(0, 1), b2 + hstepB, voffB); PG8_STAGE(PG8_SA(0, 0), a2 + hA0, voffA);
.LBB0_159:
	s_add_i32 s36, s37, 2
	s_add_u32 s78, s76, 0x80
	s_addc_u32 s79, s77, 0
	s_add_i32 s81, 0, 0x10000
	s_cmp_eq_u32 s13, s37
	s_cselect_b32 s79, s1, s79
	s_cselect_b32 s78, s0, s78
	s_cselect_b32 s83, s75, s21
	s_cselect_b32 s82, s74, s20
	s_add_i32 s37, 0, 0x14000
.Lk159_body:
	v_add_u32_e32 v96, s81, v146
	ds_read_b128 v[148:151], v96
	ds_read_b128 v[152:155], v96 offset:1024
	ds_read_b128 v[156:159], v96 offset:2048
	ds_read_b128 v[164:167], v96 offset:3072
	v_add_u32_e32 v96, s37, v146
	ds_read_b128 v[168:171], v96
	ds_read_b128 v[172:175], v96 offset:1024
	ds_read_b128 v[176:179], v96 offset:2048
	ds_read_b128 v[180:183], v96 offset:3072
	v_lshl_add_u64 v[98:99], s[76:77], 0, v[140:141]
	s_add_i32 m0, s7, 0xc000
	ds_read_b128 v[184:187], v147
	ds_read_b128 v[218:221], v147 offset:1024
	ds_read_b128 v[222:225], v147 offset:2048
	ds_read_b128 v[226:229], v147 offset:3072
	ds_read_b128 v[230:233], v147 offset:4096
	ds_read_b128 v[234:237], v147 offset:5120
	ds_read_b128 v[238:241], v147 offset:6144
	ds_read_b128 v[242:245], v147 offset:7168
	global_load_lds_dwordx4 v[98:99], off
	v_lshl_add_u64 v[98:99], s[76:77], 0, v[142:143]
	s_add_i32 m0, s7, 0xe000
	s_nop 0
	global_load_lds_dwordx4 v[98:99], off
	s_waitcnt vmcnt(8)
	s_waitcnt lgkmcnt(0)
	s_setprio 1
	v_mfma_f32_16x16x32_bf16 v[4:7], v[148:151], v[184:187], v[4:7]
	v_mfma_f32_16x16x32_bf16 v[0:3], v[156:159], v[184:187], v[0:3]
	v_mfma_f32_16x16x32_bf16 v[20:23], v[148:151], v[222:225], v[20:23]
	v_mfma_f32_16x16x32_bf16 v[16:19], v[156:159], v[222:225], v[16:19]
	s_barrier
	v_mfma_f32_16x16x32_bf16 v[36:39], v[148:151], v[230:233], v[36:39]
	v_mfma_f32_16x16x32_bf16 v[32:35], v[156:159], v[230:233], v[32:35]
	v_mfma_f32_16x16x32_bf16 v[52:55], v[148:151], v[238:241], v[52:55]
	v_mfma_f32_16x16x32_bf16 v[48:51], v[156:159], v[238:241], v[48:51]
	v_mfma_f32_16x16x32_bf16 v[4:7], v[152:155], v[218:221], v[4:7]
	v_mfma_f32_16x16x32_bf16 v[0:3], v[164:167], v[218:221], v[0:3]
	v_mfma_f32_16x16x32_bf16 v[20:23], v[152:155], v[226:229], v[20:23]
	v_mfma_f32_16x16x32_bf16 v[16:19], v[164:167], v[226:229], v[16:19]
	v_mfma_f32_16x16x32_bf16 v[36:39], v[152:155], v[234:237], v[36:39]
	v_mfma_f32_16x16x32_bf16 v[32:35], v[164:167], v[234:237], v[32:35]
	v_mfma_f32_16x16x32_bf16 v[52:55], v[152:155], v[242:245], v[52:55]
	v_mfma_f32_16x16x32_bf16 v[48:51], v[164:167], v[242:245], v[48:51]
	s_setprio 0
	s_setprio 1
	v_mfma_f32_16x16x32_bf16 v[12:15], v[168:171], v[184:187], v[12:15]
	v_mfma_f32_16x16x32_bf16 v[8:11], v[176:179], v[184:187], v[8:11]
	v_mfma_f32_16x16x32_bf16 v[28:31], v[168:171], v[222:225], v[28:31]
	v_mfma_f32_16x16x32_bf16 v[24:27], v[176:179], v[222:225], v[24:27]
	v_mfma_f32_16x16x32_bf16 v[44:47], v[168:171], v[230:233], v[44:47]
	v_mfma_f32_16x16x32_bf16 v[40:43], v[176:179], v[230:233], v[40:43]
	v_mfma_f32_16x16x32_bf16 v[60:63], v[168:171], v[238:241], v[60:63]
	v_mfma_f32_16x16x32_bf16 v[56:59], v[176:179], v[238:241], v[56:59]
	v_mfma_f32_16x16x32_bf16 v[12:15], v[172:175], v[218:221], v[12:15]
	v_mfma_f32_16x16x32_bf16 v[8:11], v[180:183], v[218:221], v[8:11]
	v_mfma_f32_16x16x32_bf16 v[28:31], v[172:175], v[226:229], v[28:31]
	v_mfma_f32_16x16x32_bf16 v[24:27], v[180:183], v[226:229], v[24:27]
	v_mfma_f32_16x16x32_bf16 v[44:47], v[172:175], v[234:237], v[44:47]
	v_mfma_f32_16x16x32_bf16 v[40:43], v[180:183], v[234:237], v[40:43]
	v_mfma_f32_16x16x32_bf16 v[60:63], v[172:175], v[242:245], v[60:63]
	v_mfma_f32_16x16x32_bf16 v[56:59], v[180:183], v[242:245], v[56:59]
	s_setprio 0
	s_barrier
	s_add_i32 s81, s81, s4
	v_lshl_add_u64 v[160:161], s[82:83], 0, v[136:137]
	s_mov_b32 m0, s81
	ds_read_b128 v[184:187], v147 offset:16384
	ds_read_b128 v[218:221], v147 offset:17408
	ds_read_b128 v[222:225], v147 offset:18432
	ds_read_b128 v[226:229], v147 offset:19456
	ds_read_b128 v[230:233], v147 offset:20480
	ds_read_b128 v[234:237], v147 offset:21504
	ds_read_b128 v[238:241], v147 offset:22528
	ds_read_b128 v[242:245], v147 offset:23552
	global_load_lds_dwordx4 v[160:161], off
	s_add_i32 m0, s81, 0x2000
	v_lshl_add_u64 v[246:247], s[82:83], 0, v[108:109]
	s_add_u32 s82, s82, s28
	s_addc_u32 s83, s83, 0
	s_add_i32 s37, s37, s4
	global_load_lds_dwordx4 v[246:247], off
	v_lshl_add_u64 v[248:249], s[82:83], 0, v[136:137]
	s_mov_b32 m0, s37
	v_lshl_add_u64 v[250:251], s[82:83], 0, v[108:109]
	global_load_lds_dwordx4 v[248:249], off
	s_add_i32 m0, s37, 0x2000
	v_lshl_add_u64 v[192:193], s[78:79], 0, v[138:139]
	global_load_lds_dwordx4 v[250:251], off
	s_mov_b32 m0, s7
	v_lshl_add_u64 v[194:195], s[78:79], 0, v[134:135]
	global_load_lds_dwordx4 v[192:193], off
	s_mov_b32 m0, s8
	s_nop 0
	global_load_lds_dwordx4 v[194:195], off
	s_waitcnt vmcnt(8)
	s_waitcnt lgkmcnt(0)
	s_setprio 1
	v_mfma_f32_16x16x32_bf16 v[68:71], v[148:151], v[184:187], v[68:71]
	v_mfma_f32_16x16x32_bf16 v[64:67], v[156:159], v[184:187], v[64:67]
	v_mfma_f32_16x16x32_bf16 v[84:87], v[148:151], v[222:225], v[84:87]
	v_mfma_f32_16x16x32_bf16 v[80:83], v[156:159], v[222:225], v[80:83]
	s_barrier
; #define PG8_STAGE(bufoff, gbase, voff) do { _Pragma("unroll") for (int _i = 0; _i < 2; ++_i) \
;         __builtin_amdgcn_global_load_lds((const unsigned*)((const char*)(gbase) + (voff)[_i]), (LAS unsigned*)(lds + (bufoff) + ldsw + _i * 8192), 16, 0, 0); } while (0)
; #define PG8_LDA(dst, b, h) do { _Pragma("unroll") for (int m = 0; m < 4; ++m) _Pragma("unroll") for (int k = 0; k < 2; ++k) dst[m][k] = *(const LAS bf16x8*)(lds + PG8_SA(b, h) + aoff + m * 2048 + k * 1024); } while (0)
; #define PG8_LDB(dst, b, h) do { _Pragma("unroll") for (int n = 0; n < 2; ++n) _Pragma("unroll") for (int k = 0; k < 2; ++k) dst[n][k] = *(const LAS bf16x8*)(lds + PG8_SB(b, h) + boff + n * 2048 + k * 1024); } while (0)
; #define PG8_MMA(ai, bj, At, Bt) do { __builtin_amdgcn_s_setprio(1); _Pragma("unroll") for (int m = 0; m < 4; ++m) _Pragma("unroll") for (int n = 0; n < 2; ++n) _Pragma("unroll") for (int k = 0; k < 2; ++k) \
;         acc[ai][bj][m][n] = __builtin_amdgcn_mfma_f32_16x16x32_bf16(Bt[n][k], At[m][k], acc[ai][bj][m][n], 0, 0, 0); __builtin_amdgcn_s_setprio(0); } while (0)
; template <class Epi, bool ALIGN_EPI, bool SP2, bool ROWHALF = false>
; DI void gemm_phase(LAS unsigned char* lds, const Gemm g, const StaticOrder& S, const Epi& E) {
;     ...
;             PG8_LDB(B0, 0, 0); PG8_LDB(B1, 0, 1); PG8_SCHED; PG8_LDA(At, 0, 0); PG8_STAGE(PG8_SA(1, 1), a1 + hA1, voffA);
;             PG8_WAIT_V(8); PG8_WAIT_L(0); PG8_BAR; PG8_MMA(0, 0, At, B0); PG8_MMA(0, 1, At, B1); PG8_BAR; PG8_SCHED;
;             if constexpr (!ROWHALF) { PG8_LDA(At, 0, 1); } PG8_STAGE(PG8_SB(0, 0), b2, voffB); PG8_STAGE(PG8_SB(0, 1), b2 + hstepB, voffB); PG8_STAGE(PG8_SA(0, 0), a2 + hA0, voffA);
;             PG8_WAIT_V(8); PG8_WAIT_L(0); PG8_BAR; if constexpr (!ROWHALF) { PG8_MMA(1, 0, At, B0); PG8_MMA(1, 1, At, B1); } PG8_BAR; PG8_SCHED;
;             PG8_LDB(B0, 1, 0); PG8_LDB(B1, 1, 1); PG8_SCHED; PG8_LDA(At, 1, 0); PG8_STAGE(PG8_SA(0, 1), a2 + hA1, voffA);
;             PG8_WAIT_V(8); PG8_WAIT_L(0); PG8_BAR; PG8_MMA(0, 0, At, B0); PG8_MMA(0, 1, At, B1); PG8_BAR; PG8_SCHED;
;             if constexpr (!ROWHALF) { PG8_LDA(At, 1, 1); } PG8_STAGE(PG8_SB(1, 0), b3, voffB); PG8_STAGE(PG8_SB(1, 1), b3 + hstepB, voffB); PG8_STAGE(PG8_SA(1, 0), a3 + hA0, voffA);
;             PG8_WAIT_V(8); PG8_WAIT_L(0); PG8_BAR; if constexpr (!ROWHALF) { PG8_MMA(1, 0, At, B0); PG8_MMA(1, 1, At, B1); } PG8_BAR; PG8_SCHED;
	v_mfma_f32_16x16x32_bf16 v[114:117], v[148:151], v[230:233], v[114:117]
	v_mfma_f32_16x16x32_bf16 v[104:107], v[156:159], v[230:233], v[104:107]
	v_mfma_f32_16x16x32_bf16 v[118:121], v[148:151], v[238:241], v[118:121]
	v_mfma_f32_16x16x32_bf16 v[110:113], v[156:159], v[238:241], v[110:113]
	v_mfma_f32_16x16x32_bf16 v[68:71], v[152:155], v[218:221], v[68:71]
	v_mfma_f32_16x16x32_bf16 v[64:67], v[164:167], v[218:221], v[64:67]
	v_mfma_f32_16x16x32_bf16 v[84:87], v[152:155], v[226:229], v[84:87]
	v_mfma_f32_16x16x32_bf16 v[80:83], v[164:167], v[226:229], v[80:83]
	v_mfma_f32_16x16x32_bf16 v[114:117], v[152:155], v[234:237], v[114:117]
	v_mfma_f32_16x16x32_bf16 v[104:107], v[164:167], v[234:237], v[104:107]
	v_mfma_f32_16x16x32_bf16 v[118:121], v[152:155], v[242:245], v[118:121]
	v_mfma_f32_16x16x32_bf16 v[110:113], v[164:167], v[242:245], v[110:113]
	s_setprio 0
	s_setprio 1
	v_mfma_f32_16x16x32_bf16 v[76:79], v[168:171], v[184:187], v[76:79]
	v_mfma_f32_16x16x32_bf16 v[72:75], v[176:179], v[184:187], v[72:75]
	v_mfma_f32_16x16x32_bf16 v[92:95], v[168:171], v[222:225], v[92:95]
	v_mfma_f32_16x16x32_bf16 v[88:91], v[176:179], v[222:225], v[88:91]
	v_mfma_f32_16x16x32_bf16 v[126:129], v[168:171], v[230:233], v[126:129]
	v_mfma_f32_16x16x32_bf16 v[122:125], v[176:179], v[230:233], v[122:125]
	v_mfma_f32_16x16x32_bf16 v[98:101], v[168:171], v[238:241], v[100:103]
	v_mfma_f32_16x16x32_bf16 v[130:133], v[176:179], v[238:241], v[130:133]
	v_mfma_f32_16x16x32_bf16 v[76:79], v[172:175], v[218:221], v[76:79]
	v_mfma_f32_16x16x32_bf16 v[72:75], v[180:183], v[218:221], v[72:75]
	v_mfma_f32_16x16x32_bf16 v[92:95], v[172:175], v[226:229], v[92:95]
	v_mfma_f32_16x16x32_bf16 v[88:91], v[180:183], v[226:229], v[88:91]
	v_mfma_f32_16x16x32_bf16 v[126:129], v[172:175], v[234:237], v[126:129]
	v_mfma_f32_16x16x32_bf16 v[122:125], v[180:183], v[234:237], v[122:125]
	v_mfma_f32_16x16x32_bf16 v[98:101], v[172:175], v[242:245], v[98:101]
	v_mfma_f32_16x16x32_bf16 v[130:133], v[180:183], v[242:245], v[130:133]
	s_setprio 0
	s_barrier
	s_add_i32 s37, 0, 0x18000
	v_add_u32_e32 v96, s37, v146
	s_add_i32 s81, 0, 0x1c000
	ds_read_b128 v[148:151], v96
	ds_read_b128 v[152:155], v96 offset:1024
	ds_read_b128 v[156:159], v96 offset:2048
	ds_read_b128 v[164:167], v96 offset:3072
	v_add_u32_e32 v96, s81, v146
	ds_read_b128 v[168:171], v96
	ds_read_b128 v[172:175], v96 offset:1024
	ds_read_b128 v[176:179], v96 offset:2048
	ds_read_b128 v[180:183], v96 offset:3072
	s_add_u32 s78, s78, s18
	s_addc_u32 s79, s79, 0
	s_mov_b32 m0, s9
	v_lshl_add_u64 v[102:103], s[78:79], 0, v[138:139]
	ds_read_b128 v[184:187], v147 offset:32768
	ds_read_b128 v[218:221], v147 offset:33792
	ds_read_b128 v[222:225], v147 offset:34816
	ds_read_b128 v[226:229], v147 offset:35840
	ds_read_b128 v[230:233], v147 offset:36864
	ds_read_b128 v[234:237], v147 offset:37888
	ds_read_b128 v[238:241], v147 offset:38912
	ds_read_b128 v[242:245], v147 offset:39936
	global_load_lds_dwordx4 v[102:103], off
	v_lshl_add_u64 v[102:103], s[78:79], 0, v[134:135]
	s_mov_b32 m0, s10
	s_nop 0
	global_load_lds_dwordx4 v[102:103], off
	s_waitcnt vmcnt(8)
	s_waitcnt lgkmcnt(0)
	s_setprio 1
	v_mfma_f32_16x16x32_bf16 v[4:7], v[148:151], v[184:187], v[4:7]
	v_mfma_f32_16x16x32_bf16 v[0:3], v[156:159], v[184:187], v[0:3]
	v_mfma_f32_16x16x32_bf16 v[20:23], v[148:151], v[222:225], v[20:23]
	v_mfma_f32_16x16x32_bf16 v[16:19], v[156:159], v[222:225], v[16:19]
	s_barrier
	v_mfma_f32_16x16x32_bf16 v[36:39], v[148:151], v[230:233], v[36:39]
	v_mfma_f32_16x16x32_bf16 v[32:35], v[156:159], v[230:233], v[32:35]
	v_mfma_f32_16x16x32_bf16 v[52:55], v[148:151], v[238:241], v[52:55]
	v_mfma_f32_16x16x32_bf16 v[48:51], v[156:159], v[238:241], v[48:51]
	v_mfma_f32_16x16x32_bf16 v[4:7], v[152:155], v[218:221], v[4:7]
	v_mfma_f32_16x16x32_bf16 v[0:3], v[164:167], v[218:221], v[0:3]
	v_mfma_f32_16x16x32_bf16 v[20:23], v[152:155], v[226:229], v[20:23]
	v_mfma_f32_16x16x32_bf16 v[16:19], v[164:167], v[226:229], v[16:19]
	v_mfma_f32_16x16x32_bf16 v[36:39], v[152:155], v[234:237], v[36:39]
	v_mfma_f32_16x16x32_bf16 v[32:35], v[164:167], v[234:237], v[32:35]
	v_mfma_f32_16x16x32_bf16 v[52:55], v[152:155], v[242:245], v[52:55]
	v_mfma_f32_16x16x32_bf16 v[48:51], v[164:167], v[242:245], v[48:51]
	s_setprio 0
	s_setprio 1
	v_mfma_f32_16x16x32_bf16 v[12:15], v[168:171], v[184:187], v[12:15]
	v_mfma_f32_16x16x32_bf16 v[8:11], v[176:179], v[184:187], v[8:11]
	v_mfma_f32_16x16x32_bf16 v[28:31], v[168:171], v[222:225], v[28:31]
	v_mfma_f32_16x16x32_bf16 v[24:27], v[176:179], v[222:225], v[24:27]
	v_mfma_f32_16x16x32_bf16 v[44:47], v[168:171], v[230:233], v[44:47]
	v_mfma_f32_16x16x32_bf16 v[40:43], v[176:179], v[230:233], v[40:43]
	v_mfma_f32_16x16x32_bf16 v[60:63], v[168:171], v[238:241], v[60:63]
	v_mfma_f32_16x16x32_bf16 v[56:59], v[176:179], v[238:241], v[56:59]
	v_mfma_f32_16x16x32_bf16 v[12:15], v[172:175], v[218:221], v[12:15]
	v_mfma_f32_16x16x32_bf16 v[8:11], v[180:183], v[218:221], v[8:11]
	v_mfma_f32_16x16x32_bf16 v[28:31], v[172:175], v[226:229], v[28:31]
	v_mfma_f32_16x16x32_bf16 v[24:27], v[180:183], v[226:229], v[24:27]
	v_mfma_f32_16x16x32_bf16 v[44:47], v[172:175], v[234:237], v[44:47]
	v_mfma_f32_16x16x32_bf16 v[40:43], v[180:183], v[234:237], v[40:43]
	v_mfma_f32_16x16x32_bf16 v[60:63], v[172:175], v[242:245], v[60:63]
	v_mfma_f32_16x16x32_bf16 v[56:59], v[180:183], v[242:245], v[56:59]
	s_setprio 0
	s_barrier
; #define PG8_STAGE(bufoff, gbase, voff) do { _Pragma("unroll") for (int _i = 0; _i < 2; ++_i) \
;         __builtin_amdgcn_global_load_lds((const unsigned*)((const char*)(gbase) + (voff)[_i]), (LAS unsigned*)(lds + (bufoff) + ldsw + _i * 8192), 16, 0, 0); } while (0)
; #define PG8_LDA(dst, b, h) do { _Pragma("unroll") for (int m = 0; m < 4; ++m) _Pragma("unroll") for (int k = 0; k < 2; ++k) dst[m][k] = *(const LAS bf16x8*)(lds + PG8_SA(b, h) + aoff + m * 2048 + k * 1024); } while (0)
; #define PG8_LDB(dst, b, h) do { _Pragma("unroll") for (int n = 0; n < 2; ++n) _Pragma("unroll") for (int k = 0; k < 2; ++k) dst[n][k] = *(const LAS bf16x8*)(lds + PG8_SB(b, h) + boff + n * 2048 + k * 1024); } while (0)
; #define PG8_MMA(ai, bj, At, Bt) do { __builtin_amdgcn_s_setprio(1); _Pragma("unroll") for (int m = 0; m < 4; ++m) _Pragma("unroll") for (int n = 0; n < 2; ++n) _Pragma("unroll") for (int k = 0; k < 2; ++k) \
;         acc[ai][bj][m][n] = __builtin_amdgcn_mfma_f32_16x16x32_bf16(Bt[n][k], At[m][k], acc[ai][bj][m][n], 0, 0, 0); __builtin_amdgcn_s_setprio(0); } while (0)
; #define PG8_WAIT_V(n) asm volatile("s_waitcnt vmcnt(" #n ")" ::: "memory")
; #define PG8_WAIT_L(n) asm volatile("s_waitcnt lgkmcnt(" #n ")" ::: "memory")
; #define PG8_BAR __builtin_amdgcn_s_barrier()
; template <class Epi, bool ALIGN_EPI, bool SP2, bool ROWHALF = false>
; DI void gemm_phase(LAS unsigned char* lds, const Gemm g, const StaticOrder& S, const Epi& E) {
;     ...
;         for (int t = 0; t < nt; t += 2) {
;             const bool last = (t == nt - 2);
;             const char* a1 = cA + (size_t)(t + 1) * kstep;
;             const char* a2 = last ? nA : cA + (size_t)(t + 2) * kstep; const char* b2 = last ? nB : cB + (size_t)(t + 2) * kstep;
;             const char* a3 = a2 + kstep; const char* b3 = b2 + kstep;
;     ...
;             PG8_LDB(B0, 1, 0); PG8_LDB(B1, 1, 1); PG8_SCHED; PG8_LDA(At, 1, 0); PG8_STAGE(PG8_SA(0, 1), a2 + hA1, voffA);
;             PG8_WAIT_V(8); PG8_WAIT_L(0); PG8_BAR; PG8_MMA(0, 0, At, B0); PG8_MMA(0, 1, At, B1); PG8_BAR; PG8_SCHED;
;             if constexpr (!ROWHALF) { PG8_LDA(At, 1, 1); } PG8_STAGE(PG8_SB(1, 0), b3, voffB); PG8_STAGE(PG8_SB(1, 1), b3 + hstepB, voffB); PG8_STAGE(PG8_SA(1, 0), a3 + hA0, voffA);
;             PG8_WAIT_V(8); PG8_WAIT_L(0); PG8_BAR; if constexpr (!ROWHALF) { PG8_MMA(1, 0, At, B0); PG8_MMA(1, 1, At, B1); } PG8_BAR; PG8_SCHED;
	s_add_i32 s37, s37, s4
	v_lshl_add_u64 v[102:103], v[160:161], 0, s[38:39]
	s_mov_b32 m0, s37
	ds_read_b128 v[184:187], v147 offset:49152
	ds_read_b128 v[218:221], v147 offset:50176
	ds_read_b128 v[222:225], v147 offset:51200
	ds_read_b128 v[226:229], v147 offset:52224
	ds_read_b128 v[230:233], v147 offset:53248
	ds_read_b128 v[234:237], v147 offset:54272
	ds_read_b128 v[238:241], v147 offset:55296
	ds_read_b128 v[242:245], v147 offset:56320
	global_load_lds_dwordx4 v[102:103], off
	v_lshl_add_u64 v[102:103], v[246:247], 0, s[38:39]
	s_add_i32 m0, s37, 0x2000
	s_add_i32 s37, s81, s4
	global_load_lds_dwordx4 v[102:103], off
	v_lshl_add_u64 v[102:103], v[248:249], 0, s[38:39]
	s_mov_b32 m0, s37
	s_nop 0
	global_load_lds_dwordx4 v[102:103], off
	v_lshl_add_u64 v[102:103], v[250:251], 0, s[38:39]
	s_add_i32 m0, s37, 0x2000
	s_nop 0
	global_load_lds_dwordx4 v[102:103], off
	v_lshl_add_u64 v[102:103], v[192:193], 0, s[38:39]
	s_mov_b32 m0, s46
	s_nop 0
	global_load_lds_dwordx4 v[102:103], off
	v_lshl_add_u64 v[102:103], v[194:195], 0, s[38:39]
	s_mov_b32 m0, s47
	s_nop 0
	global_load_lds_dwordx4 v[102:103], off
	s_waitcnt vmcnt(8)
	s_waitcnt lgkmcnt(0)
	s_setprio 1
	v_mfma_f32_16x16x32_bf16 v[68:71], v[148:151], v[184:187], v[68:71]
	v_mfma_f32_16x16x32_bf16 v[64:67], v[156:159], v[184:187], v[64:67]
	v_mfma_f32_16x16x32_bf16 v[84:87], v[148:151], v[222:225], v[84:87]
	v_mfma_f32_16x16x32_bf16 v[80:83], v[156:159], v[222:225], v[80:83]
	s_barrier
	v_mfma_f32_16x16x32_bf16 v[114:117], v[148:151], v[230:233], v[114:117]
	v_mfma_f32_16x16x32_bf16 v[102:105], v[156:159], v[230:233], v[104:107]
	v_mfma_f32_16x16x32_bf16 v[118:121], v[148:151], v[238:241], v[118:121]
	v_mfma_f32_16x16x32_bf16 v[110:113], v[156:159], v[238:241], v[110:113]
	v_mfma_f32_16x16x32_bf16 v[68:71], v[152:155], v[218:221], v[68:71]
	v_mfma_f32_16x16x32_bf16 v[64:67], v[164:167], v[218:221], v[64:67]
	v_mfma_f32_16x16x32_bf16 v[84:87], v[152:155], v[226:229], v[84:87]
	v_mfma_f32_16x16x32_bf16 v[80:83], v[164:167], v[226:229], v[80:83]
	v_mfma_f32_16x16x32_bf16 v[114:117], v[152:155], v[234:237], v[114:117]
	v_mfma_f32_16x16x32_bf16 v[104:107], v[164:167], v[234:237], v[102:105]
	v_mfma_f32_16x16x32_bf16 v[118:121], v[152:155], v[242:245], v[118:121]
	v_mfma_f32_16x16x32_bf16 v[110:113], v[164:167], v[242:245], v[110:113]
	s_setprio 0
	s_setprio 1
	v_mfma_f32_16x16x32_bf16 v[76:79], v[168:171], v[184:187], v[76:79]
	s_add_u32 s76, s76, 0x100
	s_addc_u32 s77, s77, 0
	v_mfma_f32_16x16x32_bf16 v[72:75], v[176:179], v[184:187], v[72:75]
	s_add_u32 s20, s20, 0x100
	s_addc_u32 s21, s21, 0
	v_mfma_f32_16x16x32_bf16 v[92:95], v[168:171], v[222:225], v[92:95]
	s_mov_b32 s37, s36
	s_add_i32 s36, s37, 2
	v_mfma_f32_16x16x32_bf16 v[88:91], v[176:179], v[222:225], v[88:91]
	s_add_u32 s78, s76, 0x80
	s_addc_u32 s79, s77, 0
	v_mfma_f32_16x16x32_bf16 v[126:129], v[168:171], v[230:233], v[126:129]
	s_cmp_eq_u32 s13, s37
	s_cselect_b32 s79, s1, s79
	v_mfma_f32_16x16x32_bf16 v[122:125], v[176:179], v[230:233], v[122:125]
	s_cselect_b32 s78, s0, s78
	s_cselect_b32 s83, s75, s21
	v_mfma_f32_16x16x32_bf16 v[98:101], v[168:171], v[238:241], v[98:101]
	s_cselect_b32 s82, s74, s20
	s_add_i32 s81, 0, 0x10000
	v_mfma_f32_16x16x32_bf16 v[130:133], v[176:179], v[238:241], v[130:133]
	v_mfma_f32_16x16x32_bf16 v[76:79], v[172:175], v[218:221], v[76:79]
	v_mfma_f32_16x16x32_bf16 v[72:75], v[180:183], v[218:221], v[72:75]
	v_mfma_f32_16x16x32_bf16 v[92:95], v[172:175], v[226:229], v[92:95]
	v_mfma_f32_16x16x32_bf16 v[88:91], v[180:183], v[226:229], v[88:91]
	v_mfma_f32_16x16x32_bf16 v[126:129], v[172:175], v[234:237], v[126:129]
	v_mfma_f32_16x16x32_bf16 v[122:125], v[180:183], v[234:237], v[122:125]
	v_mfma_f32_16x16x32_bf16 v[100:103], v[172:175], v[242:245], v[98:101]
	v_mfma_f32_16x16x32_bf16 v[130:133], v[180:183], v[242:245], v[130:133]
	s_setprio 0
	s_cmp_ge_u32 s37, s29
	s_mov_b32 s37, 0x14000
	s_barrier
	s_cbranch_scc0 .Lk159_body
	v_mov_b32_e32 v248, v217
	v_mov_b32_e32 v250, v207
	v_mov_b32_e32 v207, v196
	v_mov_b32_e32 v196, v197
	v_mov_b32_e32 v197, v198
	v_mov_b32_e32 v198, v199
	v_mov_b32_e32 v199, v200
	v_mov_b32_e32 v200, v201
	v_mov_b32_e32 v201, v202
	v_mov_b32_e32 v202, v203
	v_mov_b32_e32 v203, v204
	v_mov_b32_e32 v204, v205
	v_mov_b32_e32 v205, v206
	s_and_b64 vcc, exec, s[42:43]
	s_cbranch_vccnz .LBB0_152
	s_branch .LBB0_164
